# cvhost LDS transpose strict waits + nt hint on the hosted bf16 stores
# speedup vs baseline: 1.0049x; 1.0049x over previous
; #define GAS __attribute__((address_space(1)))
; __device__ __forceinline__ unsigned cvt_pk_bf16(float lo, float hi) { unsigned r; asm volatile("v_cvt_pk_bf16_f32 %0, %1, %2" : "=v"(r) : "v"(lo), "v"(hi)); return r; }
; template <int NB>
; __device__ __forceinline__ void p0_batch(int it0, int stride, int lane, const P0Ptrs& a) {
;     ...
;     for (int q = 0; q < NB; ++q) {
;         const float gs = d[q].gs; const bool hk = d[q].ks != nullptr;
;         const f32x4 t0 = hk ? s0[q] * gs : (f32x4){gs, gs, gs, gs}, t1 = hk ? s1[q] * gs : (f32x4){gs, gs, gs, gs};
; #pragma unroll
;         for (int i = 0; i < 4; ++i) { v[q][i] *= t0[i]; v[q][4 + i] *= t1[i]; }
;         if (d[q].dst) {
; #pragma unroll
;             for (int e = 0; e < 4; ++e) { u32x4 o; o.x = cvt_pk_bf16(v[q][0][e], v[q][1][e]); o.y = cvt_pk_bf16(v[q][2][e], v[q][3][e]); o.z = cvt_pk_bf16(v[q][4][e], v[q][5][e]); o.w = cvt_pk_bf16(v[q][6][e], v[q][7][e]);
;                 *(GAS u32x4*)(d[q].dst + (size_t)e * d[q].ldt) = o; } }
;     }
.Lcv_nomul:
	v_readfirstlane_b32 s98, v0
	v_and_b32_e32 v76, 63, v0
	v_lshrrev_b32_e32 v77, 2, v76
	v_and_b32_e32 v78, 3, v76
	s_lshr_b32 s98, s98, 6
	s_lshl_b32 s99, s98, 10
	s_cmp_lt_u32 s98, 6
	s_mov_b32 s98, 0x24c00
	s_cselect_b32 s98, 0x1e800, s98
	s_add_i32 s98, s98, s99
	v_lshlrev_b32_e32 v81, 8, v78
	v_lshl_add_u32 v81, v77, 2, v81
	v_add_u32_e32 v81, s98, v81
	v_lshl_add_u32 v82, v76, 4, s98
	v_lshlrev_b32_e32 v83, 3, v78
	v_mad_u32_u24 v83, v77, s91, v83
	ds_write_b32 v81, v238
	ds_write_b32 v81, v239 offset:64
	ds_write_b32 v81, v240 offset:128
	ds_write_b32 v81, v241 offset:192
	ds_read_b128 v[100:103], v82
	ds_write_b32 v81, v242
	ds_write_b32 v81, v243 offset:64
	ds_write_b32 v81, v244 offset:128
	ds_write_b32 v81, v245 offset:192
	ds_read_b128 v[104:107], v82
	s_lshl_b32 s98, s91, 4
	s_add_u32 s98, s92, s98
	s_addc_u32 s99, s93, 0
	s_waitcnt lgkmcnt(0)
	v_cvt_pk_bf16_f32 v100, v100, v101
	v_cvt_pk_bf16_f32 v101, v102, v103
	v_cvt_pk_bf16_f32 v104, v104, v105
	v_cvt_pk_bf16_f32 v105, v106, v107
	global_store_dwordx2 v83, v[100:101], s[92:93] nt
	global_store_dwordx2 v83, v[104:105], s[98:99] nt
	s_add_u32 s92, s92, 32
	s_addc_u32 s93, s93, 0
